# final epilogue: nt hint on read-once residual loads and write-once output stores (on v48)
# baseline (speedup 1.0000x reference)
;     __device__ __forceinline__ void operator()(const f32x4 (&acc)[2][2][4][2], const pg8::Unit& u, int wr, int wc, int fr, int fq) const { if (u.job) kv(acc, u, wr, wc, fr, fq); else q(acc, u, wr, wc, fr, fq); }
;     __device__ __forceinline__ void operator()(const f32x4 (&acc)[2][2][4][2], const pg8::Unit& u, int wr, int wc, int fr, int fq) const { if (u.job) e1(acc, u, wr, wc, fr, fq); else e0(acc, u, wr, wc, fr, fq); }
;     __device__ __forceinline__ void operator()(const f32x4 (&acc)[2][2][4][2], const pg8::Unit& u, int wr, int wc, int fr, int fq) const {
;         const int row0 = u.pm * 256 + wr * 64 + fr; const int col0 = u.pn * 256 + wc * 32 + 8 * fq;
; #pragma unroll
;         for (int ai = 0; ai < 2; ++ai)
; #pragma unroll
;             for (int m = 0; m < 4; ++m)
; #pragma unroll
;                 for (int bj = 0; bj < 2; ++bj) {
;                     const size_t off = (size_t)(row0 + ai * 128 + m * 16) * 2048 + col0 + bj * 128;
;                     const f32x4 x0 = *(const f32x4*)(X + off), x1 = *(const f32x4*)(X + off + 4);
;                     *(f32x4*)(O + off) = x0 + acc[ai][bj][m][0]; *(f32x4*)(O + off + 4) = x1 + acc[ai][bj][m][1];
;                 }
.LBB0_1247:
	v_lshl_add_u32 v193, s48, 8, v146
	v_lshl_or_b32 v140, s44, 8, v148
	v_lshlrev_b32_e32 v140, 2, v140
	v_lshl_add_u32 v140, v193, 13, v140
	v_add_u32_e32 v141, 0x20000, v140
	v_add_u32_e32 v142, 0x40000, v140
	v_add_u32_e32 v143, 0x60000, v140
	v_add_u32_e32 v144, 0x100000, v140
	v_add_u32_e32 v145, 0x120000, v140
	v_add_u32_e32 v182, 0x140000, v140
	v_add_u32_e32 v183, 0x160000, v140
	s_nop 15
	s_nop 3
	s_andn2_b64 vcc, exec, s[4:5]
	global_load_dwordx4 v[150:153], v140, s[8:9] nt
	global_load_dwordx4 v[154:157], v140, s[8:9] offset:16 nt
	global_load_dwordx4 v[158:161], v140, s[8:9] offset:512 nt
	global_load_dwordx4 v[162:165], v140, s[8:9] offset:528 nt
	global_load_dwordx4 v[166:169], v141, s[8:9] nt
	global_load_dwordx4 v[170:173], v141, s[8:9] offset:16 nt
	global_load_dwordx4 v[174:177], v141, s[8:9] offset:512 nt
	global_load_dwordx4 v[178:181], v141, s[8:9] offset:528 nt
	global_load_dwordx4 v[202:205], v142, s[8:9] nt
	global_load_dwordx4 v[206:209], v142, s[8:9] offset:16 nt
	global_load_dwordx4 v[210:213], v142, s[8:9] offset:512 nt
	global_load_dwordx4 v[214:217], v142, s[8:9] offset:528 nt
	global_load_dwordx4 v[218:221], v143, s[8:9] nt
	global_load_dwordx4 v[222:225], v143, s[8:9] offset:16 nt
	global_load_dwordx4 v[226:229], v143, s[8:9] offset:512 nt
	global_load_dwordx4 v[230:233], v143, s[8:9] offset:528 nt
	s_waitcnt vmcnt(14)
	v_pk_add_f32 v[124:125], v[124:125], v[150:151]
	v_pk_add_f32 v[126:127], v[126:127], v[152:153]
	v_pk_add_f32 v[120:121], v[120:121], v[154:155]
	v_pk_add_f32 v[122:123], v[122:123], v[156:157]
	global_store_dwordx4 v140, v[124:127], s[12:13] nt
	global_store_dwordx4 v140, v[120:123], s[12:13] offset:16 nt
	global_load_dwordx4 v[150:153], v144, s[8:9] nt
	global_load_dwordx4 v[154:157], v144, s[8:9] offset:16 nt
	s_waitcnt vmcnt(16)
	v_pk_add_f32 v[116:117], v[116:117], v[158:159]
	v_pk_add_f32 v[118:119], v[118:119], v[160:161]
	v_pk_add_f32 v[112:113], v[112:113], v[162:163]
	v_pk_add_f32 v[114:115], v[114:115], v[164:165]
	global_store_dwordx4 v140, v[116:119], s[12:13] offset:512 nt
	global_store_dwordx4 v140, v[112:115], s[12:13] offset:528 nt
	global_load_dwordx4 v[158:161], v144, s[8:9] offset:512 nt
	global_load_dwordx4 v[162:165], v144, s[8:9] offset:528 nt
	s_waitcnt vmcnt(18)
	v_pk_add_f32 v[108:109], v[108:109], v[166:167]
	v_pk_add_f32 v[110:111], v[110:111], v[168:169]
	v_pk_add_f32 v[104:105], v[104:105], v[170:171]
	v_pk_add_f32 v[106:107], v[106:107], v[172:173]
	global_store_dwordx4 v141, v[108:111], s[12:13] nt
	global_store_dwordx4 v141, v[104:107], s[12:13] offset:16 nt
	global_load_dwordx4 v[166:169], v145, s[8:9] nt
	global_load_dwordx4 v[170:173], v145, s[8:9] offset:16 nt
	s_waitcnt vmcnt(20)
	v_pk_add_f32 v[100:101], v[100:101], v[174:175]
	v_pk_add_f32 v[102:103], v[102:103], v[176:177]
	v_pk_add_f32 v[96:97], v[96:97], v[178:179]
	v_pk_add_f32 v[98:99], v[98:99], v[180:181]
	global_store_dwordx4 v141, v[100:103], s[12:13] offset:512 nt
	global_store_dwordx4 v141, v[96:99], s[12:13] offset:528 nt
	global_load_dwordx4 v[174:177], v145, s[8:9] offset:512 nt
	global_load_dwordx4 v[178:181], v145, s[8:9] offset:528 nt
	s_waitcnt vmcnt(22)
	v_pk_add_f32 v[92:93], v[92:93], v[202:203]
	v_pk_add_f32 v[94:95], v[94:95], v[204:205]
	v_pk_add_f32 v[88:89], v[88:89], v[206:207]
	v_pk_add_f32 v[90:91], v[90:91], v[208:209]
	global_store_dwordx4 v142, v[92:95], s[12:13] nt
	global_store_dwordx4 v142, v[88:91], s[12:13] offset:16 nt
	global_load_dwordx4 v[202:205], v182, s[8:9] nt
	global_load_dwordx4 v[206:209], v182, s[8:9] offset:16 nt
	s_waitcnt vmcnt(24)
;     __device__ __forceinline__ void operator()(const f32x4 (&acc)[2][2][4][2], const pg8::Unit& u, int wr, int wc, int fr, int fq) const { if (u.job) kv(acc, u, wr, wc, fr, fq); else q(acc, u, wr, wc, fr, fq); }
;     __device__ __forceinline__ void operator()(const f32x4 (&acc)[2][2][4][2], const pg8::Unit& u, int wr, int wc, int fr, int fq) const { if (u.job) e1(acc, u, wr, wc, fr, fq); else e0(acc, u, wr, wc, fr, fq); }
;     __device__ __forceinline__ void operator()(const f32x4 (&acc)[2][2][4][2], const pg8::Unit& u, int wr, int wc, int fr, int fq) const {
;         const int row0 = u.pm * 256 + wr * 64 + fr; const int col0 = u.pn * 256 + wc * 32 + 8 * fq;
; #pragma unroll
;         for (int ai = 0; ai < 2; ++ai)
; #pragma unroll
;             for (int m = 0; m < 4; ++m)
; #pragma unroll
;                 for (int bj = 0; bj < 2; ++bj) {
;                     const size_t off = (size_t)(row0 + ai * 128 + m * 16) * 2048 + col0 + bj * 128;
;                     const f32x4 x0 = *(const f32x4*)(X + off), x1 = *(const f32x4*)(X + off + 4);
;                     *(f32x4*)(O + off) = x0 + acc[ai][bj][m][0]; *(f32x4*)(O + off + 4) = x1 + acc[ai][bj][m][1];
;                 }
	v_pk_add_f32 v[84:85], v[84:85], v[210:211]
	v_pk_add_f32 v[86:87], v[86:87], v[212:213]
	v_pk_add_f32 v[80:81], v[80:81], v[214:215]
	v_pk_add_f32 v[82:83], v[82:83], v[216:217]
	global_store_dwordx4 v142, v[84:87], s[12:13] offset:512 nt
	global_store_dwordx4 v142, v[80:83], s[12:13] offset:528 nt
	global_load_dwordx4 v[210:213], v182, s[8:9] offset:512 nt
	global_load_dwordx4 v[214:217], v182, s[8:9] offset:528 nt
	s_waitcnt vmcnt(26)
	v_pk_add_f32 v[76:77], v[76:77], v[218:219]
	v_pk_add_f32 v[78:79], v[78:79], v[220:221]
	v_pk_add_f32 v[72:73], v[72:73], v[222:223]
	v_pk_add_f32 v[74:75], v[74:75], v[224:225]
	global_store_dwordx4 v143, v[76:79], s[12:13] nt
	global_store_dwordx4 v143, v[72:75], s[12:13] offset:16 nt
	global_load_dwordx4 v[218:221], v183, s[8:9] nt
	global_load_dwordx4 v[222:225], v183, s[8:9] offset:16 nt
	s_waitcnt vmcnt(28)
	v_pk_add_f32 v[68:69], v[68:69], v[226:227]
	v_pk_add_f32 v[70:71], v[70:71], v[228:229]
	v_pk_add_f32 v[64:65], v[64:65], v[230:231]
	v_pk_add_f32 v[66:67], v[66:67], v[232:233]
	global_store_dwordx4 v143, v[68:71], s[12:13] offset:512 nt
	global_store_dwordx4 v143, v[64:67], s[12:13] offset:528 nt
	global_load_dwordx4 v[226:229], v183, s[8:9] offset:512 nt
	global_load_dwordx4 v[230:233], v183, s[8:9] offset:528 nt
	s_waitcnt vmcnt(28)
	v_pk_add_f32 v[60:61], v[60:61], v[150:151]
	v_pk_add_f32 v[62:63], v[62:63], v[152:153]
	v_pk_add_f32 v[56:57], v[56:57], v[154:155]
	v_pk_add_f32 v[58:59], v[58:59], v[156:157]
	global_store_dwordx4 v144, v[60:63], s[12:13] nt
	global_store_dwordx4 v144, v[56:59], s[12:13] offset:16 nt
	s_waitcnt vmcnt(26)
	v_pk_add_f32 v[52:53], v[52:53], v[158:159]
	v_pk_add_f32 v[54:55], v[54:55], v[160:161]
	v_pk_add_f32 v[48:49], v[48:49], v[162:163]
	v_pk_add_f32 v[50:51], v[50:51], v[164:165]
	global_store_dwordx4 v144, v[52:55], s[12:13] offset:512 nt
	global_store_dwordx4 v144, v[48:51], s[12:13] offset:528 nt
	s_waitcnt vmcnt(24)
	v_pk_add_f32 v[44:45], v[44:45], v[166:167]
	v_pk_add_f32 v[46:47], v[46:47], v[168:169]
	v_pk_add_f32 v[40:41], v[40:41], v[170:171]
	v_pk_add_f32 v[42:43], v[42:43], v[172:173]
	global_store_dwordx4 v145, v[44:47], s[12:13] nt
	global_store_dwordx4 v145, v[40:43], s[12:13] offset:16 nt
	s_waitcnt vmcnt(22)
	v_pk_add_f32 v[36:37], v[36:37], v[174:175]
	v_pk_add_f32 v[38:39], v[38:39], v[176:177]
	v_pk_add_f32 v[32:33], v[32:33], v[178:179]
	v_pk_add_f32 v[34:35], v[34:35], v[180:181]
	global_store_dwordx4 v145, v[36:39], s[12:13] offset:512 nt
	global_store_dwordx4 v145, v[32:35], s[12:13] offset:528 nt
	s_waitcnt vmcnt(20)
	v_pk_add_f32 v[28:29], v[28:29], v[202:203]
	v_pk_add_f32 v[30:31], v[30:31], v[204:205]
	v_pk_add_f32 v[24:25], v[24:25], v[206:207]
	v_pk_add_f32 v[26:27], v[26:27], v[208:209]
	global_store_dwordx4 v182, v[28:31], s[12:13] nt
	global_store_dwordx4 v182, v[24:27], s[12:13] offset:16 nt
	s_waitcnt vmcnt(18)
	v_pk_add_f32 v[20:21], v[20:21], v[210:211]
	v_pk_add_f32 v[22:23], v[22:23], v[212:213]
	v_pk_add_f32 v[16:17], v[16:17], v[214:215]
	v_pk_add_f32 v[18:19], v[18:19], v[216:217]
	global_store_dwordx4 v182, v[20:23], s[12:13] offset:512 nt
	global_store_dwordx4 v182, v[16:19], s[12:13] offset:528 nt
	s_waitcnt vmcnt(16)
	v_pk_add_f32 v[12:13], v[12:13], v[218:219]
	v_pk_add_f32 v[14:15], v[14:15], v[220:221]
	v_pk_add_f32 v[8:9], v[8:9], v[222:223]
	v_pk_add_f32 v[10:11], v[10:11], v[224:225]
	global_store_dwordx4 v183, v[12:15], s[12:13] nt
	global_store_dwordx4 v183, v[8:11], s[12:13] offset:16 nt
	s_waitcnt vmcnt(14)
	v_pk_add_f32 v[4:5], v[4:5], v[226:227]
	v_pk_add_f32 v[6:7], v[6:7], v[228:229]
	v_pk_add_f32 v[0:1], v[0:1], v[230:231]
	v_pk_add_f32 v[2:3], v[2:3], v[232:233]
	global_store_dwordx4 v183, v[4:7], s[12:13] offset:512 nt
	global_store_dwordx4 v183, v[0:3], s[12:13] offset:528 nt
	s_mov_b64 s[34:35], -1
	s_cbranch_vccnz .LBB0_1236
	s_andn2_b64 vcc, exec, s[6:7]
	s_cbranch_vccnz .LBB0_1235
	s_barrier
	s_branch .LBB0_1235
